# EpiBf16: rstd partial-sum loads for 7 of 8 row groups hoisted to epilogue start (both paths)
# baseline (speedup 1.0000x reference)
; __device__ __forceinline__ float rstd_from(const float* ps, int row, int off4, int n4, float inv_dim, int fq) {
;     float s = 0.f;
;     if (fq < n4) { const f32x4 v = *((const f32x4*)(ps + (size_t)row * 16) + off4 + fq); s = (v[0] + v[1]) + (v[2] + v[3]); }
;     __device__ __forceinline__ void operator()(const f32x4 (&acc)[2][2][4][2], const Unit& u, int wr, int wc, int fr, int fq) const {
;     ...
; #pragma unroll
;         for (int ai = 0; ai < 2; ++ai)
; #pragma unroll
;             for (int m = 0; m < 4; ++m) {
;                 const int row = row0 + ai * HALF + m * 16;
;                 const float rs = rstd_from(ps_in, row, off4, n4, inv_dim, fq); float ss = 0.f;
.LBB0_719:
	v_lshl_add_u32 v198, s7, 8, v178
	v_ashrrev_i32_e32 v199, 31, v198
	v_lshlrev_b64 v[198:199], 6, v[198:199]
	v_lshl_add_u64 v[198:199], v[138:139], 0, v[198:199]
	s_and_saveexec_b64 s[20:21], s[40:41]
	global_load_dwordx4 v[190:193], v[198:199], off offset:1024
	global_load_dwordx4 v[194:197], v[198:199], off offset:2048
	global_load_dwordx4 v[218:221], v[198:199], off offset:3072
	v_add_co_u32_e32 v198, vcc, 0x2000, v198
	s_nop 1
	v_addc_co_u32_e32 v199, vcc, 0, v199, vcc
	global_load_dwordx4 v[222:225], v[198:199], off
	global_load_dwordx4 v[226:229], v[198:199], off offset:1024
	global_load_dwordx4 v[230:233], v[198:199], off offset:2048
	global_load_dwordx4 v[234:237], v[198:199], off offset:3072
	s_or_b64 exec, exec, s[20:21]
	v_readlane_b32 s20, v255, 35
	v_lshl_add_u32 v148, s7, 8, v178
	v_readlane_b32 s21, v255, 36
	s_lshl_b32 s7, s2, 8
	s_mov_b64 s[0:1], -1
	s_andn2_b64 vcc, exec, s[20:21]
	v_ashrrev_i32_e32 v149, 31, v148
	s_cbranch_vccnz .LBB0_898
	v_mov_b32_e32 v150, 0
	s_and_saveexec_b64 s[0:1], s[40:41]
	s_cbranch_execz .LBB0_722
	v_lshlrev_b64 v[150:151], 6, v[148:149]
	v_lshl_add_u64 v[150:151], v[138:139], 0, v[150:151]
	global_load_dwordx4 v[150:153], v[150:151], off
	s_waitcnt vmcnt(0)
	v_mov_b32_e32 v154, v151
	v_mov_b32_e32 v155, v152
	v_mov_b32_e32 v151, v153
	v_pk_add_f32 v[150:151], v[154:155], v[150:151]
	s_nop 0
	v_add_f32_e32 v150, v150, v151

; __device__ __forceinline__ float rstd_from(const float* ps, int row, int off4, int n4, float inv_dim, int fq) {
;     float s = 0.f;
;     if (fq < n4) { const f32x4 v = *((const f32x4*)(ps + (size_t)row * 16) + off4 + fq); s = (v[0] + v[1]) + (v[2] + v[3]); }
;     __device__ __forceinline__ void operator()(const f32x4 (&acc)[2][2][4][2], const Unit& u, int wr, int wc, int fr, int fq) const {
;     ...
;                 const int row = row0 + ai * HALF + m * 16;
;                 const float rs = rstd_from(ps_in, row, off4, n4, inv_dim, fq); float ss = 0.f;
.LBB0_742:
	v_or_b32_e32 v152, 16, v148
	s_waitcnt lgkmcnt(0)
	v_ashrrev_i32_e32 v153, 31, v152
	v_mov_b32_e32 v154, 0
	s_and_saveexec_b64 s[58:59], s[40:41]
	s_cbranch_execz .LBB0_744
	v_lshlrev_b64 v[154:155], 6, v[152:153]
	v_lshl_add_u64 v[154:155], v[138:139], 0, v[154:155]
	v_mov_b32_e32 v154, v190
	v_mov_b32_e32 v155, v191
	v_mov_b32_e32 v156, v192
	v_mov_b32_e32 v157, v193
	v_mov_b32_e32 v158, v155
	v_mov_b32_e32 v159, v156
	v_mov_b32_e32 v155, v157
	v_pk_add_f32 v[154:155], v[158:159], v[154:155]
	s_nop 0
	v_add_f32_e32 v154, v154, v155

; __device__ __forceinline__ float rstd_from(const float* ps, int row, int off4, int n4, float inv_dim, int fq) {
;     float s = 0.f;
;     if (fq < n4) { const f32x4 v = *((const f32x4*)(ps + (size_t)row * 16) + off4 + fq); s = (v[0] + v[1]) + (v[2] + v[3]); }
;     __device__ __forceinline__ void operator()(const f32x4 (&acc)[2][2][4][2], const Unit& u, int wr, int wc, int fr, int fq) const {
;     ...
;                 const int row = row0 + ai * HALF + m * 16;
;                 const float rs = rstd_from(ps_in, row, off4, n4, inv_dim, fq); float ss = 0.f;
.LBB0_764:
	v_or_b32_e32 v152, 32, v148
	v_ashrrev_i32_e32 v153, 31, v152
	v_mov_b32_e32 v154, 0
	s_and_saveexec_b64 s[58:59], s[40:41]
	s_cbranch_execz .LBB0_766
	s_waitcnt lgkmcnt(0)
	v_lshlrev_b64 v[154:155], 6, v[152:153]
	v_lshl_add_u64 v[154:155], v[138:139], 0, v[154:155]
	v_mov_b32_e32 v154, v194
	v_mov_b32_e32 v155, v195
	v_mov_b32_e32 v156, v196
	v_mov_b32_e32 v157, v197
	v_mov_b32_e32 v158, v155
	v_mov_b32_e32 v159, v156
	v_mov_b32_e32 v155, v157
	v_pk_add_f32 v[154:155], v[158:159], v[154:155]
	s_nop 0
	v_add_f32_e32 v154, v154, v155

; __device__ __forceinline__ float rstd_from(const float* ps, int row, int off4, int n4, float inv_dim, int fq) {
;     float s = 0.f;
;     if (fq < n4) { const f32x4 v = *((const f32x4*)(ps + (size_t)row * 16) + off4 + fq); s = (v[0] + v[1]) + (v[2] + v[3]); }
;     __device__ __forceinline__ void operator()(const f32x4 (&acc)[2][2][4][2], const Unit& u, int wr, int wc, int fr, int fq) const {
;     ...
;                 const int row = row0 + ai * HALF + m * 16;
;                 const float rs = rstd_from(ps_in, row, off4, n4, inv_dim, fq); float ss = 0.f;
.LBB0_786:
	v_or_b32_e32 v152, 48, v148
	v_ashrrev_i32_e32 v153, 31, v152
	v_mov_b32_e32 v154, 0
	s_and_saveexec_b64 s[58:59], s[40:41]
	s_cbranch_execz .LBB0_788
	s_waitcnt lgkmcnt(0)
	v_lshlrev_b64 v[154:155], 6, v[152:153]
	v_lshl_add_u64 v[154:155], v[138:139], 0, v[154:155]
	v_mov_b32_e32 v154, v218
	v_mov_b32_e32 v155, v219
	v_mov_b32_e32 v156, v220
	v_mov_b32_e32 v157, v221
	v_mov_b32_e32 v158, v155
	v_mov_b32_e32 v159, v156
	v_mov_b32_e32 v155, v157
	v_pk_add_f32 v[154:155], v[158:159], v[154:155]
	s_nop 0
	v_add_f32_e32 v154, v154, v155

; __device__ __forceinline__ float rstd_from(const float* ps, int row, int off4, int n4, float inv_dim, int fq) {
;     float s = 0.f;
;     if (fq < n4) { const f32x4 v = *((const f32x4*)(ps + (size_t)row * 16) + off4 + fq); s = (v[0] + v[1]) + (v[2] + v[3]); }
;     __device__ __forceinline__ void operator()(const f32x4 (&acc)[2][2][4][2], const Unit& u, int wr, int wc, int fr, int fq) const {
;     ...
;                 const int row = row0 + ai * HALF + m * 16;
;                 const float rs = rstd_from(ps_in, row, off4, n4, inv_dim, fq); float ss = 0.f;
.LBB0_808:
	v_add_u32_e32 v152, 0x80, v148
	v_ashrrev_i32_e32 v153, 31, v152
	v_mov_b32_e32 v154, 0
	s_and_saveexec_b64 s[58:59], s[40:41]
	s_cbranch_execz .LBB0_810
	s_waitcnt lgkmcnt(0)
	v_lshlrev_b64 v[154:155], 6, v[152:153]
	v_lshl_add_u64 v[154:155], v[138:139], 0, v[154:155]
	v_mov_b32_e32 v154, v222
	v_mov_b32_e32 v155, v223
	v_mov_b32_e32 v156, v224
	v_mov_b32_e32 v157, v225
	v_mov_b32_e32 v158, v155
	v_mov_b32_e32 v159, v156
	v_mov_b32_e32 v155, v157
	v_pk_add_f32 v[154:155], v[158:159], v[154:155]
	s_nop 0
	v_add_f32_e32 v154, v154, v155

; __device__ __forceinline__ float rstd_from(const float* ps, int row, int off4, int n4, float inv_dim, int fq) {
;     float s = 0.f;
;     if (fq < n4) { const f32x4 v = *((const f32x4*)(ps + (size_t)row * 16) + off4 + fq); s = (v[0] + v[1]) + (v[2] + v[3]); }
;     __device__ __forceinline__ void operator()(const f32x4 (&acc)[2][2][4][2], const Unit& u, int wr, int wc, int fr, int fq) const {
;     ...
;                 const int row = row0 + ai * HALF + m * 16;
;                 const float rs = rstd_from(ps_in, row, off4, n4, inv_dim, fq); float ss = 0.f;
.LBB0_830:
	v_add_u32_e32 v152, 0x90, v148
	v_ashrrev_i32_e32 v153, 31, v152
	v_mov_b32_e32 v154, 0
	s_and_saveexec_b64 s[58:59], s[40:41]
	s_cbranch_execz .LBB0_832
	s_waitcnt lgkmcnt(0)
	v_lshlrev_b64 v[154:155], 6, v[152:153]
	v_lshl_add_u64 v[154:155], v[138:139], 0, v[154:155]
	v_mov_b32_e32 v154, v226
	v_mov_b32_e32 v155, v227
	v_mov_b32_e32 v156, v228
	v_mov_b32_e32 v157, v229
	v_mov_b32_e32 v158, v155
	v_mov_b32_e32 v159, v156
	v_mov_b32_e32 v155, v157
	v_pk_add_f32 v[154:155], v[158:159], v[154:155]
	s_nop 0
	v_add_f32_e32 v154, v154, v155

; __device__ __forceinline__ float rstd_from(const float* ps, int row, int off4, int n4, float inv_dim, int fq) {
;     float s = 0.f;
;     if (fq < n4) { const f32x4 v = *((const f32x4*)(ps + (size_t)row * 16) + off4 + fq); s = (v[0] + v[1]) + (v[2] + v[3]); }
;     __device__ __forceinline__ void operator()(const f32x4 (&acc)[2][2][4][2], const Unit& u, int wr, int wc, int fr, int fq) const {
;     ...
;                 const int row = row0 + ai * HALF + m * 16;
;                 const float rs = rstd_from(ps_in, row, off4, n4, inv_dim, fq); float ss = 0.f;
.LBB0_852:
	v_add_u32_e32 v152, 0xa0, v148
	v_ashrrev_i32_e32 v153, 31, v152
	v_mov_b32_e32 v154, 0
	s_and_saveexec_b64 s[58:59], s[40:41]
	s_cbranch_execz .LBB0_854
	s_waitcnt lgkmcnt(0)
	v_lshlrev_b64 v[154:155], 6, v[152:153]
	v_lshl_add_u64 v[154:155], v[138:139], 0, v[154:155]
	v_mov_b32_e32 v154, v230
	v_mov_b32_e32 v155, v231
	v_mov_b32_e32 v156, v232
	v_mov_b32_e32 v157, v233
	v_mov_b32_e32 v158, v155
	v_mov_b32_e32 v159, v156
	v_mov_b32_e32 v155, v157
	v_pk_add_f32 v[154:155], v[158:159], v[154:155]
	s_nop 0
	v_add_f32_e32 v154, v154, v155

; __device__ __forceinline__ float rstd_from(const float* ps, int row, int off4, int n4, float inv_dim, int fq) {
;     float s = 0.f;
;     if (fq < n4) { const f32x4 v = *((const f32x4*)(ps + (size_t)row * 16) + off4 + fq); s = (v[0] + v[1]) + (v[2] + v[3]); }
;     __device__ __forceinline__ void operator()(const f32x4 (&acc)[2][2][4][2], const Unit& u, int wr, int wc, int fr, int fq) const {
;     ...
;                 const int row = row0 + ai * HALF + m * 16;
;                 const float rs = rstd_from(ps_in, row, off4, n4, inv_dim, fq); float ss = 0.f;
.LBB0_874:
	v_add_u32_e32 v152, 0xb0, v148
	v_ashrrev_i32_e32 v153, 31, v152
	v_mov_b32_e32 v154, 0
	s_and_saveexec_b64 s[58:59], s[40:41]
	s_cbranch_execz .LBB0_876
	s_waitcnt lgkmcnt(0)
	v_lshlrev_b64 v[154:155], 6, v[152:153]
	v_lshl_add_u64 v[154:155], v[138:139], 0, v[154:155]
	v_mov_b32_e32 v154, v234
	v_mov_b32_e32 v155, v235
	v_mov_b32_e32 v156, v236
	v_mov_b32_e32 v157, v237
	v_mov_b32_e32 v158, v155
	v_mov_b32_e32 v159, v156
	v_mov_b32_e32 v155, v157
	v_pk_add_f32 v[154:155], v[158:159], v[154:155]
	s_nop 0
	v_add_f32_e32 v154, v154, v155

; __device__ __forceinline__ unsigned cvt_pk_bf16(float lo, float hi) { unsigned r; asm volatile("v_cvt_pk_bf16_f32 %0, %1, %2" : "=v"(r) : "v"(lo), "v"(hi)); return r; }
;     __device__ __forceinline__ void operator()(const f32x4 (&acc)[2][2][4][2], const Unit& u, int wr, int wc, int fr, int fq) const {
;     ...
;                     const int row = row0 + ai * HALF + m * 16;
;                     const float rs = rstd_from(ps_in, row, off4, n4, inv_dim, fq);
;                     f32x4 v[2][2]; float ss = 0.f;
; #pragma unroll
;                     for (int bj = 0; bj < 2; ++bj) { v[bj][0] = acc[ai][bj][m][0] * rs; v[bj][1] = acc[ai][bj][m][1] * rs;
;                         ss += (v[bj][0][0] * v[bj][0][0] + v[bj][0][1] * v[bj][0][1]) + (v[bj][0][2] * v[bj][0][2] + v[bj][0][3] * v[bj][0][3]) + (v[bj][1][0] * v[bj][1][0] + v[bj][1][1] * v[bj][1][1]) + (v[bj][1][2] * v[bj][1][2] + v[bj][1][3] * v[bj][1][3]); }
;                     ss += __shfl_xor(ss, 16); ss += __shfl_xor(ss, 32);
;                     const float rh = ttype < 2 ? rsqrtf(ss * (1.f / 64.f) + 1e-6f) : 1.f;
; #pragma unroll
;                     for (int bj = 0; bj < 2; ++bj) {
;                         u32x4 w; w.x = cvt_pk_bf16(v[bj][0][0] * rh * gv[bj][0], v[bj][0][1] * rh * gv[bj][1]); w.y = cvt_pk_bf16(v[bj][0][2] * rh * gv[bj][2], v[bj][0][3] * rh * gv[bj][3]);
;                         w.z = cvt_pk_bf16(v[bj][1][0] * rh * gv[bj][4], v[bj][1][1] * rh * gv[bj][5]); w.w = cvt_pk_bf16(v[bj][1][2] * rh * gv[bj][6], v[bj][1][3] * rh * gv[bj][7]);
;                         *(u32x4*)(O + (size_t)row * ldc + colo + 32 * bj) = w;
.LBB0_967:
	v_mul_f32_e32 v124, v124, v173
	v_mul_f32_e32 v125, v125, v173
	v_mul_f32_e32 v122, v122, v173
	v_mul_f32_e32 v123, v123, v173
	v_mul_f32_e32 v150, v150, v173
	v_mul_f32_e32 v151, v151, v173
	v_mul_f32_e32 v126, v126, v173
	v_mul_f32_e32 v127, v127, v173
	s_waitcnt vmcnt(0)
	v_mul_f32_e32 v124, v156, v124
	v_mul_f32_e32 v125, v157, v125
	v_mul_f32_e32 v122, v158, v122
	v_mul_f32_e32 v123, v159, v123
	v_lshl_or_b32 v112, s69, 6, v136
	v_mul_f32_e32 v150, v152, v150
	v_mul_f32_e32 v151, v153, v151
	v_cvt_pk_bf16_f32 v174, v150, v151
	v_mul_f32_e32 v126, v154, v126
	v_mul_f32_e32 v127, v155, v127
	v_cvt_pk_bf16_f32 v175, v126, v127
	v_cvt_pk_bf16_f32 v176, v124, v125
	v_cvt_pk_bf16_f32 v177, v122, v123
	v_mul_lo_u32 v124, s77, v148
	v_mul_lo_u32 v125, s76, v149
	v_mad_u64_u32 v[122:123], s[0:1], s76, v148, 0
	v_or_b32_e32 v112, s7, v112
	v_add3_u32 v123, v123, v125, v124
	s_waitcnt lgkmcnt(0)
	v_ashrrev_i32_e32 v113, 31, v112
	v_lshl_add_u64 v[122:123], v[122:123], 1, s[80:81]
	v_mul_f32_e32 v120, v120, v173
	v_mul_f32_e32 v121, v121, v173
	v_mul_f32_e32 v114, v114, v173
	v_lshl_add_u64 v[124:125], v[112:113], 1, v[122:123]
	v_mul_f32_e32 v120, v160, v120
	v_mul_f32_e32 v121, v161, v121
	v_mul_f32_e32 v118, v118, v173
	v_mul_f32_e32 v119, v119, v173
	v_mul_f32_e32 v116, v116, v173
	v_mul_f32_e32 v117, v117, v173
	v_mul_f32_e32 v114, v166, v114
	v_mul_f32_e32 v115, v115, v173
	global_store_dwordx4 v[124:125], v[174:177], off
	v_cvt_pk_bf16_f32 v120, v120, v121
	v_mul_f32_e32 v118, v162, v118
	v_mul_f32_e32 v119, v163, v119
	v_cvt_pk_bf16_f32 v121, v118, v119
	v_mul_f32_e32 v116, v164, v116
	v_mul_f32_e32 v117, v165, v117
	v_cvt_pk_bf16_f32 v122, v116, v117
	v_mul_f32_e32 v115, v167, v115
	v_cvt_pk_bf16_f32 v123, v114, v115
	v_or_b32_e32 v114, 16, v148
	v_mov_b32_e32 v116, 0
	v_ashrrev_i32_e32 v115, 31, v114
	global_store_dwordx4 v[124:125], v[120:123], off offset:64
	s_and_saveexec_b64 s[0:1], s[40:41]
	s_cbranch_execz .LBB0_969
	v_lshlrev_b64 v[116:117], 6, v[114:115]
	v_lshl_add_u64 v[116:117], v[138:139], 0, v[116:117]
	v_mov_b32_e32 v116, v190
	v_mov_b32_e32 v117, v191
	v_mov_b32_e32 v118, v192
	v_mov_b32_e32 v119, v193
	v_mov_b32_e32 v120, v117
	v_mov_b32_e32 v121, v118
	v_mov_b32_e32 v117, v119
	v_pk_add_f32 v[116:117], v[120:121], v[116:117]
	s_nop 0
	v_add_f32_e32 v116, v116, v117

; __device__ __forceinline__ unsigned cvt_pk_bf16(float lo, float hi) { unsigned r; asm volatile("v_cvt_pk_bf16_f32 %0, %1, %2" : "=v"(r) : "v"(lo), "v"(hi)); return r; }
;     __device__ __forceinline__ void operator()(const f32x4 (&acc)[2][2][4][2], const Unit& u, int wr, int wc, int fr, int fq) const {
;     ...
;                     const int row = row0 + ai * HALF + m * 16;
;                     const float rs = rstd_from(ps_in, row, off4, n4, inv_dim, fq);
;                     f32x4 v[2][2]; float ss = 0.f;
; #pragma unroll
;                     for (int bj = 0; bj < 2; ++bj) { v[bj][0] = acc[ai][bj][m][0] * rs; v[bj][1] = acc[ai][bj][m][1] * rs;
;                         ss += (v[bj][0][0] * v[bj][0][0] + v[bj][0][1] * v[bj][0][1]) + (v[bj][0][2] * v[bj][0][2] + v[bj][0][3] * v[bj][0][3]) + (v[bj][1][0] * v[bj][1][0] + v[bj][1][1] * v[bj][1][1]) + (v[bj][1][2] * v[bj][1][2] + v[bj][1][3] * v[bj][1][3]); }
;                     ss += __shfl_xor(ss, 16); ss += __shfl_xor(ss, 32);
;                     const float rh = ttype < 2 ? rsqrtf(ss * (1.f / 64.f) + 1e-6f) : 1.f;
; #pragma unroll
;                     for (int bj = 0; bj < 2; ++bj) {
;                         u32x4 w; w.x = cvt_pk_bf16(v[bj][0][0] * rh * gv[bj][0], v[bj][0][1] * rh * gv[bj][1]); w.y = cvt_pk_bf16(v[bj][0][2] * rh * gv[bj][2], v[bj][0][3] * rh * gv[bj][3]);
;                         w.z = cvt_pk_bf16(v[bj][1][0] * rh * gv[bj][4], v[bj][1][1] * rh * gv[bj][5]); w.w = cvt_pk_bf16(v[bj][1][2] * rh * gv[bj][6], v[bj][1][3] * rh * gv[bj][7]);
;                         *(u32x4*)(O + (size_t)row * ldc + colo + 32 * bj) = w;
.LBB0_971:
	v_mul_f32_e32 v108, v108, v116
	v_mul_f32_e32 v109, v109, v116
	v_mul_f32_e32 v108, v152, v108
	v_mul_f32_e32 v109, v153, v109
	v_cvt_pk_bf16_f32 v108, v108, v109
	v_mul_f32_e32 v109, v110, v116
	v_mul_f32_e32 v110, v111, v116
	v_mul_f32_e32 v104, v104, v116
	v_mul_f32_e32 v105, v105, v116
	v_mul_f32_e32 v109, v154, v109
	v_mul_f32_e32 v110, v155, v110
	v_mul_f32_e32 v104, v156, v104
	v_mul_f32_e32 v105, v157, v105
	v_cvt_pk_bf16_f32 v109, v109, v110
	v_cvt_pk_bf16_f32 v110, v104, v105
	v_mul_f32_e32 v104, v106, v116
	v_mul_f32_e32 v105, v107, v116
	v_mul_f32_e32 v104, v158, v104
	v_mul_f32_e32 v105, v159, v105
	v_cvt_pk_bf16_f32 v111, v104, v105
	v_mul_lo_u32 v106, s77, v114
	v_mul_lo_u32 v107, s76, v115
	v_mad_u64_u32 v[104:105], s[0:1], s76, v114, 0
	v_add3_u32 v105, v105, v107, v106
	v_lshl_add_u64 v[104:105], v[104:105], 1, s[80:81]
	v_mul_f32_e32 v100, v100, v116
	v_mul_f32_e32 v101, v101, v116
	v_lshl_add_u64 v[104:105], v[112:113], 1, v[104:105]
	v_mul_f32_e32 v100, v160, v100
	v_mul_f32_e32 v101, v161, v101
	global_store_dwordx4 v[104:105], v[108:111], off
	v_cvt_pk_bf16_f32 v100, v100, v101
	v_mul_f32_e32 v101, v102, v116
	v_mul_f32_e32 v102, v103, v116
	v_mul_f32_e32 v96, v96, v116
	v_mul_f32_e32 v101, v162, v101
	v_mul_f32_e32 v102, v163, v102
	v_mul_f32_e32 v96, v164, v96
	v_mul_f32_e32 v97, v97, v116
	v_cvt_pk_bf16_f32 v101, v101, v102
	v_mul_f32_e32 v97, v165, v97
	v_cvt_pk_bf16_f32 v102, v96, v97
	v_mul_f32_e32 v96, v98, v116
	v_mul_f32_e32 v96, v166, v96
	v_mul_f32_e32 v97, v99, v116
	v_mul_f32_e32 v97, v167, v97
	v_cvt_pk_bf16_f32 v103, v96, v97
	v_or_b32_e32 v96, 32, v148
	v_mov_b32_e32 v98, 0
	v_ashrrev_i32_e32 v97, 31, v96
	global_store_dwordx4 v[104:105], v[100:103], off offset:64
	s_and_saveexec_b64 s[0:1], s[40:41]
	s_cbranch_execz .LBB0_973
	v_lshlrev_b64 v[98:99], 6, v[96:97]
	v_lshl_add_u64 v[98:99], v[138:139], 0, v[98:99]
	v_mov_b32_e32 v98, v194
	v_mov_b32_e32 v99, v195
	v_mov_b32_e32 v100, v196
	v_mov_b32_e32 v101, v197
	v_mov_b32_e32 v102, v99
	v_mov_b32_e32 v103, v100
	v_mov_b32_e32 v99, v101
	v_pk_add_f32 v[98:99], v[102:103], v[98:99]
	s_nop 0
	v_add_f32_e32 v98, v98, v99

; __device__ __forceinline__ unsigned cvt_pk_bf16(float lo, float hi) { unsigned r; asm volatile("v_cvt_pk_bf16_f32 %0, %1, %2" : "=v"(r) : "v"(lo), "v"(hi)); return r; }
;     __device__ __forceinline__ void operator()(const f32x4 (&acc)[2][2][4][2], const Unit& u, int wr, int wc, int fr, int fq) const {
;     ...
;                     const int row = row0 + ai * HALF + m * 16;
;                     const float rs = rstd_from(ps_in, row, off4, n4, inv_dim, fq);
;                     f32x4 v[2][2]; float ss = 0.f;
; #pragma unroll
;                     for (int bj = 0; bj < 2; ++bj) { v[bj][0] = acc[ai][bj][m][0] * rs; v[bj][1] = acc[ai][bj][m][1] * rs;
;                         ss += (v[bj][0][0] * v[bj][0][0] + v[bj][0][1] * v[bj][0][1]) + (v[bj][0][2] * v[bj][0][2] + v[bj][0][3] * v[bj][0][3]) + (v[bj][1][0] * v[bj][1][0] + v[bj][1][1] * v[bj][1][1]) + (v[bj][1][2] * v[bj][1][2] + v[bj][1][3] * v[bj][1][3]); }
;                     ss += __shfl_xor(ss, 16); ss += __shfl_xor(ss, 32);
;                     const float rh = ttype < 2 ? rsqrtf(ss * (1.f / 64.f) + 1e-6f) : 1.f;
; #pragma unroll
;                     for (int bj = 0; bj < 2; ++bj) {
;                         u32x4 w; w.x = cvt_pk_bf16(v[bj][0][0] * rh * gv[bj][0], v[bj][0][1] * rh * gv[bj][1]); w.y = cvt_pk_bf16(v[bj][0][2] * rh * gv[bj][2], v[bj][0][3] * rh * gv[bj][3]);
;                         w.z = cvt_pk_bf16(v[bj][1][0] * rh * gv[bj][4], v[bj][1][1] * rh * gv[bj][5]); w.w = cvt_pk_bf16(v[bj][1][2] * rh * gv[bj][6], v[bj][1][3] * rh * gv[bj][7]);
;                         *(u32x4*)(O + (size_t)row * ldc + colo + 32 * bj) = w;
.LBB0_975:
	v_mul_f32_e32 v92, v92, v98
	v_mul_f32_e32 v93, v93, v98
	v_mul_f32_e32 v92, v152, v92
	v_mul_f32_e32 v93, v153, v93
	v_cvt_pk_bf16_f32 v92, v92, v93
	v_mul_f32_e32 v93, v94, v98
	v_mul_f32_e32 v94, v95, v98
	v_mul_f32_e32 v88, v88, v98
	v_mul_f32_e32 v89, v89, v98
	v_mul_f32_e32 v93, v154, v93
	v_mul_f32_e32 v94, v155, v94
	v_mul_f32_e32 v88, v156, v88
	v_mul_f32_e32 v89, v157, v89
	v_cvt_pk_bf16_f32 v93, v93, v94
	v_cvt_pk_bf16_f32 v94, v88, v89
	v_mul_f32_e32 v88, v90, v98
	v_mul_f32_e32 v89, v91, v98
	v_mul_f32_e32 v88, v158, v88
	v_mul_f32_e32 v89, v159, v89
	v_cvt_pk_bf16_f32 v95, v88, v89
	v_mul_lo_u32 v90, s77, v96
	v_mul_lo_u32 v91, s76, v97
	v_mad_u64_u32 v[88:89], s[0:1], s76, v96, 0
	v_add3_u32 v89, v89, v91, v90
	v_lshl_add_u64 v[88:89], v[88:89], 1, s[80:81]
	v_mul_f32_e32 v84, v84, v98
	v_mul_f32_e32 v85, v85, v98
	v_lshl_add_u64 v[88:89], v[112:113], 1, v[88:89]
	v_mul_f32_e32 v84, v160, v84
	v_mul_f32_e32 v85, v161, v85
	global_store_dwordx4 v[88:89], v[92:95], off
	v_cvt_pk_bf16_f32 v84, v84, v85
	v_mul_f32_e32 v85, v86, v98
	v_mul_f32_e32 v86, v87, v98
	v_mul_f32_e32 v80, v80, v98
	v_mul_f32_e32 v85, v162, v85
	v_mul_f32_e32 v86, v163, v86
	v_mul_f32_e32 v80, v164, v80
	v_mul_f32_e32 v81, v81, v98
	v_cvt_pk_bf16_f32 v85, v85, v86
	v_mul_f32_e32 v81, v165, v81
	v_cvt_pk_bf16_f32 v86, v80, v81
	v_mul_f32_e32 v80, v82, v98
	v_mul_f32_e32 v80, v166, v80
	v_mul_f32_e32 v81, v83, v98
	v_mul_f32_e32 v81, v167, v81
	v_cvt_pk_bf16_f32 v87, v80, v81
	v_or_b32_e32 v80, 48, v148
	v_mov_b32_e32 v82, 0
	v_ashrrev_i32_e32 v81, 31, v80
	global_store_dwordx4 v[88:89], v[84:87], off offset:64
	s_and_saveexec_b64 s[0:1], s[40:41]
	s_cbranch_execz .LBB0_977
	v_lshlrev_b64 v[82:83], 6, v[80:81]
	v_lshl_add_u64 v[82:83], v[138:139], 0, v[82:83]
	v_mov_b32_e32 v82, v218
	v_mov_b32_e32 v83, v219
	v_mov_b32_e32 v84, v220
	v_mov_b32_e32 v85, v221
	v_mov_b32_e32 v86, v83
	v_mov_b32_e32 v87, v84
	v_mov_b32_e32 v83, v85
	v_pk_add_f32 v[82:83], v[86:87], v[82:83]
	s_nop 0
	v_add_f32_e32 v82, v82, v83

; __device__ __forceinline__ unsigned cvt_pk_bf16(float lo, float hi) { unsigned r; asm volatile("v_cvt_pk_bf16_f32 %0, %1, %2" : "=v"(r) : "v"(lo), "v"(hi)); return r; }
;     __device__ __forceinline__ void operator()(const f32x4 (&acc)[2][2][4][2], const Unit& u, int wr, int wc, int fr, int fq) const {
;     ...
;                     const int row = row0 + ai * HALF + m * 16;
;                     const float rs = rstd_from(ps_in, row, off4, n4, inv_dim, fq);
;                     f32x4 v[2][2]; float ss = 0.f;
; #pragma unroll
;                     for (int bj = 0; bj < 2; ++bj) { v[bj][0] = acc[ai][bj][m][0] * rs; v[bj][1] = acc[ai][bj][m][1] * rs;
;                         ss += (v[bj][0][0] * v[bj][0][0] + v[bj][0][1] * v[bj][0][1]) + (v[bj][0][2] * v[bj][0][2] + v[bj][0][3] * v[bj][0][3]) + (v[bj][1][0] * v[bj][1][0] + v[bj][1][1] * v[bj][1][1]) + (v[bj][1][2] * v[bj][1][2] + v[bj][1][3] * v[bj][1][3]); }
;                     ss += __shfl_xor(ss, 16); ss += __shfl_xor(ss, 32);
;                     const float rh = ttype < 2 ? rsqrtf(ss * (1.f / 64.f) + 1e-6f) : 1.f;
; #pragma unroll
;                     for (int bj = 0; bj < 2; ++bj) {
;                         u32x4 w; w.x = cvt_pk_bf16(v[bj][0][0] * rh * gv[bj][0], v[bj][0][1] * rh * gv[bj][1]); w.y = cvt_pk_bf16(v[bj][0][2] * rh * gv[bj][2], v[bj][0][3] * rh * gv[bj][3]);
;                         w.z = cvt_pk_bf16(v[bj][1][0] * rh * gv[bj][4], v[bj][1][1] * rh * gv[bj][5]); w.w = cvt_pk_bf16(v[bj][1][2] * rh * gv[bj][6], v[bj][1][3] * rh * gv[bj][7]);
;                         *(u32x4*)(O + (size_t)row * ldc + colo + 32 * bj) = w;
.LBB0_979:
	v_mul_f32_e32 v76, v76, v82
	v_mul_f32_e32 v77, v77, v82
	v_mul_f32_e32 v76, v152, v76
	v_mul_f32_e32 v77, v153, v77
	v_cvt_pk_bf16_f32 v76, v76, v77
	v_mul_f32_e32 v77, v78, v82
	v_mul_f32_e32 v78, v79, v82
	v_mul_f32_e32 v72, v72, v82
	v_mul_f32_e32 v73, v73, v82
	v_mul_f32_e32 v77, v154, v77
	v_mul_f32_e32 v78, v155, v78
	v_mul_f32_e32 v72, v156, v72
	v_mul_f32_e32 v73, v157, v73
	v_cvt_pk_bf16_f32 v77, v77, v78
	v_cvt_pk_bf16_f32 v78, v72, v73
	v_mul_f32_e32 v72, v74, v82
	v_mul_f32_e32 v73, v75, v82
	v_mul_f32_e32 v72, v158, v72
	v_mul_f32_e32 v73, v159, v73
	v_cvt_pk_bf16_f32 v79, v72, v73
	v_mul_lo_u32 v74, s77, v80
	v_mul_lo_u32 v75, s76, v81
	v_mad_u64_u32 v[72:73], s[0:1], s76, v80, 0
	v_add3_u32 v73, v73, v75, v74
	v_lshl_add_u64 v[72:73], v[72:73], 1, s[80:81]
	v_mul_f32_e32 v68, v68, v82
	v_mul_f32_e32 v69, v69, v82
	v_lshl_add_u64 v[72:73], v[112:113], 1, v[72:73]
	v_mul_f32_e32 v68, v160, v68
	v_mul_f32_e32 v69, v161, v69
	global_store_dwordx4 v[72:73], v[76:79], off
	v_cvt_pk_bf16_f32 v68, v68, v69
	v_mul_f32_e32 v69, v70, v82
	v_mul_f32_e32 v70, v71, v82
	v_mul_f32_e32 v64, v64, v82
	v_mul_f32_e32 v69, v162, v69
	v_mul_f32_e32 v70, v163, v70
	v_mul_f32_e32 v64, v164, v64
	v_mul_f32_e32 v65, v65, v82
	v_cvt_pk_bf16_f32 v69, v69, v70
	v_mul_f32_e32 v65, v165, v65
	v_cvt_pk_bf16_f32 v70, v64, v65
	v_mul_f32_e32 v64, v66, v82
	v_mul_f32_e32 v64, v166, v64
	v_mul_f32_e32 v65, v67, v82
	v_mul_f32_e32 v65, v167, v65
	v_cvt_pk_bf16_f32 v71, v64, v65
	v_add_u32_e32 v64, 0x80, v148
	v_mov_b32_e32 v66, 0
	v_ashrrev_i32_e32 v65, 31, v64
	global_store_dwordx4 v[72:73], v[68:71], off offset:64
	s_and_saveexec_b64 s[0:1], s[40:41]
	s_cbranch_execz .LBB0_981
	v_lshlrev_b64 v[66:67], 6, v[64:65]
	v_lshl_add_u64 v[66:67], v[138:139], 0, v[66:67]
	v_mov_b32_e32 v66, v222
	v_mov_b32_e32 v67, v223
	v_mov_b32_e32 v68, v224
	v_mov_b32_e32 v69, v225
	v_mov_b32_e32 v70, v67
	v_mov_b32_e32 v71, v68
	v_mov_b32_e32 v67, v69
	v_pk_add_f32 v[66:67], v[70:71], v[66:67]
	s_nop 0
	v_add_f32_e32 v66, v66, v67

; __device__ __forceinline__ unsigned cvt_pk_bf16(float lo, float hi) { unsigned r; asm volatile("v_cvt_pk_bf16_f32 %0, %1, %2" : "=v"(r) : "v"(lo), "v"(hi)); return r; }
;     __device__ __forceinline__ void operator()(const f32x4 (&acc)[2][2][4][2], const Unit& u, int wr, int wc, int fr, int fq) const {
;     ...
;                     const int row = row0 + ai * HALF + m * 16;
;                     const float rs = rstd_from(ps_in, row, off4, n4, inv_dim, fq);
;                     f32x4 v[2][2]; float ss = 0.f;
; #pragma unroll
;                     for (int bj = 0; bj < 2; ++bj) { v[bj][0] = acc[ai][bj][m][0] * rs; v[bj][1] = acc[ai][bj][m][1] * rs;
;                         ss += (v[bj][0][0] * v[bj][0][0] + v[bj][0][1] * v[bj][0][1]) + (v[bj][0][2] * v[bj][0][2] + v[bj][0][3] * v[bj][0][3]) + (v[bj][1][0] * v[bj][1][0] + v[bj][1][1] * v[bj][1][1]) + (v[bj][1][2] * v[bj][1][2] + v[bj][1][3] * v[bj][1][3]); }
;                     ss += __shfl_xor(ss, 16); ss += __shfl_xor(ss, 32);
;                     const float rh = ttype < 2 ? rsqrtf(ss * (1.f / 64.f) + 1e-6f) : 1.f;
; #pragma unroll
;                     for (int bj = 0; bj < 2; ++bj) {
;                         u32x4 w; w.x = cvt_pk_bf16(v[bj][0][0] * rh * gv[bj][0], v[bj][0][1] * rh * gv[bj][1]); w.y = cvt_pk_bf16(v[bj][0][2] * rh * gv[bj][2], v[bj][0][3] * rh * gv[bj][3]);
;                         w.z = cvt_pk_bf16(v[bj][1][0] * rh * gv[bj][4], v[bj][1][1] * rh * gv[bj][5]); w.w = cvt_pk_bf16(v[bj][1][2] * rh * gv[bj][6], v[bj][1][3] * rh * gv[bj][7]);
;                         *(u32x4*)(O + (size_t)row * ldc + colo + 32 * bj) = w;
.LBB0_983:
	v_mul_f32_e32 v60, v60, v66
	v_mul_f32_e32 v61, v61, v66
	v_mul_f32_e32 v60, v152, v60
	v_mul_f32_e32 v61, v153, v61
	v_cvt_pk_bf16_f32 v60, v60, v61
	v_mul_f32_e32 v61, v62, v66
	v_mul_f32_e32 v62, v63, v66
	v_mul_f32_e32 v56, v56, v66
	v_mul_f32_e32 v57, v57, v66
	v_mul_f32_e32 v61, v154, v61
	v_mul_f32_e32 v62, v155, v62
	v_mul_f32_e32 v56, v156, v56
	v_mul_f32_e32 v57, v157, v57
	v_cvt_pk_bf16_f32 v61, v61, v62
	v_cvt_pk_bf16_f32 v62, v56, v57
	v_mul_f32_e32 v56, v58, v66
	v_mul_f32_e32 v57, v59, v66
	v_mul_f32_e32 v56, v158, v56
	v_mul_f32_e32 v57, v159, v57
	v_cvt_pk_bf16_f32 v63, v56, v57
	v_mul_lo_u32 v58, s77, v64
	v_mul_lo_u32 v59, s76, v65
	v_mad_u64_u32 v[56:57], s[0:1], s76, v64, 0
	v_add3_u32 v57, v57, v59, v58
	v_lshl_add_u64 v[56:57], v[56:57], 1, s[80:81]
	v_mul_f32_e32 v52, v52, v66
	v_mul_f32_e32 v53, v53, v66
	v_lshl_add_u64 v[56:57], v[112:113], 1, v[56:57]
	v_mul_f32_e32 v52, v160, v52
	v_mul_f32_e32 v53, v161, v53
	global_store_dwordx4 v[56:57], v[60:63], off
	v_cvt_pk_bf16_f32 v52, v52, v53
	v_mul_f32_e32 v53, v54, v66
	v_mul_f32_e32 v54, v55, v66
	v_mul_f32_e32 v48, v48, v66
	v_mul_f32_e32 v53, v162, v53
	v_mul_f32_e32 v54, v163, v54
	v_mul_f32_e32 v48, v164, v48
	v_mul_f32_e32 v49, v49, v66
	v_cvt_pk_bf16_f32 v53, v53, v54
	v_mul_f32_e32 v49, v165, v49
	v_cvt_pk_bf16_f32 v54, v48, v49
	v_mul_f32_e32 v48, v50, v66
	v_mul_f32_e32 v48, v166, v48
	v_mul_f32_e32 v49, v51, v66
	v_mul_f32_e32 v49, v167, v49
	v_cvt_pk_bf16_f32 v55, v48, v49
	v_add_u32_e32 v48, 0x90, v148
	v_mov_b32_e32 v50, 0
	v_ashrrev_i32_e32 v49, 31, v48
	global_store_dwordx4 v[56:57], v[52:55], off offset:64
	s_and_saveexec_b64 s[0:1], s[40:41]
	s_cbranch_execz .LBB0_985
	v_lshlrev_b64 v[50:51], 6, v[48:49]
	v_lshl_add_u64 v[50:51], v[138:139], 0, v[50:51]
	v_mov_b32_e32 v50, v226
	v_mov_b32_e32 v51, v227
	v_mov_b32_e32 v52, v228
	v_mov_b32_e32 v53, v229
	v_mov_b32_e32 v54, v51
	v_mov_b32_e32 v55, v52
	v_mov_b32_e32 v51, v53
	v_pk_add_f32 v[50:51], v[54:55], v[50:51]
	s_nop 0
	v_add_f32_e32 v50, v50, v51

; __device__ __forceinline__ unsigned cvt_pk_bf16(float lo, float hi) { unsigned r; asm volatile("v_cvt_pk_bf16_f32 %0, %1, %2" : "=v"(r) : "v"(lo), "v"(hi)); return r; }
;     __device__ __forceinline__ void operator()(const f32x4 (&acc)[2][2][4][2], const Unit& u, int wr, int wc, int fr, int fq) const {
;     ...
;                     const int row = row0 + ai * HALF + m * 16;
;                     const float rs = rstd_from(ps_in, row, off4, n4, inv_dim, fq);
;                     f32x4 v[2][2]; float ss = 0.f;
; #pragma unroll
;                     for (int bj = 0; bj < 2; ++bj) { v[bj][0] = acc[ai][bj][m][0] * rs; v[bj][1] = acc[ai][bj][m][1] * rs;
;                         ss += (v[bj][0][0] * v[bj][0][0] + v[bj][0][1] * v[bj][0][1]) + (v[bj][0][2] * v[bj][0][2] + v[bj][0][3] * v[bj][0][3]) + (v[bj][1][0] * v[bj][1][0] + v[bj][1][1] * v[bj][1][1]) + (v[bj][1][2] * v[bj][1][2] + v[bj][1][3] * v[bj][1][3]); }
;                     ss += __shfl_xor(ss, 16); ss += __shfl_xor(ss, 32);
;                     const float rh = ttype < 2 ? rsqrtf(ss * (1.f / 64.f) + 1e-6f) : 1.f;
; #pragma unroll
;                     for (int bj = 0; bj < 2; ++bj) {
;                         u32x4 w; w.x = cvt_pk_bf16(v[bj][0][0] * rh * gv[bj][0], v[bj][0][1] * rh * gv[bj][1]); w.y = cvt_pk_bf16(v[bj][0][2] * rh * gv[bj][2], v[bj][0][3] * rh * gv[bj][3]);
;                         w.z = cvt_pk_bf16(v[bj][1][0] * rh * gv[bj][4], v[bj][1][1] * rh * gv[bj][5]); w.w = cvt_pk_bf16(v[bj][1][2] * rh * gv[bj][6], v[bj][1][3] * rh * gv[bj][7]);
;                         *(u32x4*)(O + (size_t)row * ldc + colo + 32 * bj) = w;
.LBB0_987:
	v_mul_f32_e32 v44, v44, v50
	v_mul_f32_e32 v45, v45, v50
	v_mul_f32_e32 v44, v152, v44
	v_mul_f32_e32 v45, v153, v45
	v_cvt_pk_bf16_f32 v44, v44, v45
	v_mul_f32_e32 v45, v46, v50
	v_mul_f32_e32 v46, v47, v50
	v_mul_f32_e32 v40, v40, v50
	v_mul_f32_e32 v41, v41, v50
	v_mul_f32_e32 v45, v154, v45
	v_mul_f32_e32 v46, v155, v46
	v_mul_f32_e32 v40, v156, v40
	v_mul_f32_e32 v41, v157, v41
	v_cvt_pk_bf16_f32 v45, v45, v46
	v_cvt_pk_bf16_f32 v46, v40, v41
	v_mul_f32_e32 v40, v42, v50
	v_mul_f32_e32 v41, v43, v50
	v_mul_f32_e32 v40, v158, v40
	v_mul_f32_e32 v41, v159, v41
	v_cvt_pk_bf16_f32 v47, v40, v41
	v_mul_lo_u32 v42, s77, v48
	v_mul_lo_u32 v43, s76, v49
	v_mad_u64_u32 v[40:41], s[0:1], s76, v48, 0
	v_add3_u32 v41, v41, v43, v42
	v_lshl_add_u64 v[40:41], v[40:41], 1, s[80:81]
	v_mul_f32_e32 v36, v36, v50
	v_mul_f32_e32 v37, v37, v50
	v_lshl_add_u64 v[40:41], v[112:113], 1, v[40:41]
	v_mul_f32_e32 v36, v160, v36
	v_mul_f32_e32 v37, v161, v37
	global_store_dwordx4 v[40:41], v[44:47], off
	v_cvt_pk_bf16_f32 v36, v36, v37
	v_mul_f32_e32 v37, v38, v50
	v_mul_f32_e32 v38, v39, v50
	v_mul_f32_e32 v32, v32, v50
	v_mul_f32_e32 v37, v162, v37
	v_mul_f32_e32 v38, v163, v38
	v_mul_f32_e32 v32, v164, v32
	v_mul_f32_e32 v33, v33, v50
	v_cvt_pk_bf16_f32 v37, v37, v38
	v_mul_f32_e32 v33, v165, v33
	v_cvt_pk_bf16_f32 v38, v32, v33
	v_mul_f32_e32 v32, v34, v50
	v_mul_f32_e32 v32, v166, v32
	v_mul_f32_e32 v33, v35, v50
	v_mul_f32_e32 v33, v167, v33
	v_cvt_pk_bf16_f32 v39, v32, v33
	v_add_u32_e32 v32, 0xa0, v148
	v_mov_b32_e32 v34, 0
	v_ashrrev_i32_e32 v33, 31, v32
	global_store_dwordx4 v[40:41], v[36:39], off offset:64
	s_and_saveexec_b64 s[0:1], s[40:41]
	s_cbranch_execz .LBB0_989
	v_lshlrev_b64 v[34:35], 6, v[32:33]
	v_lshl_add_u64 v[34:35], v[138:139], 0, v[34:35]
	v_mov_b32_e32 v34, v230
	v_mov_b32_e32 v35, v231
	v_mov_b32_e32 v36, v232
	v_mov_b32_e32 v37, v233
	v_mov_b32_e32 v38, v35
	v_mov_b32_e32 v39, v36
	v_mov_b32_e32 v35, v37
	v_pk_add_f32 v[34:35], v[38:39], v[34:35]
	s_nop 0
	v_add_f32_e32 v34, v34, v35

; __device__ __forceinline__ unsigned cvt_pk_bf16(float lo, float hi) { unsigned r; asm volatile("v_cvt_pk_bf16_f32 %0, %1, %2" : "=v"(r) : "v"(lo), "v"(hi)); return r; }
;     __device__ __forceinline__ void operator()(const f32x4 (&acc)[2][2][4][2], const Unit& u, int wr, int wc, int fr, int fq) const {
;     ...
;                     const int row = row0 + ai * HALF + m * 16;
;                     const float rs = rstd_from(ps_in, row, off4, n4, inv_dim, fq);
;                     f32x4 v[2][2]; float ss = 0.f;
; #pragma unroll
;                     for (int bj = 0; bj < 2; ++bj) { v[bj][0] = acc[ai][bj][m][0] * rs; v[bj][1] = acc[ai][bj][m][1] * rs;
;                         ss += (v[bj][0][0] * v[bj][0][0] + v[bj][0][1] * v[bj][0][1]) + (v[bj][0][2] * v[bj][0][2] + v[bj][0][3] * v[bj][0][3]) + (v[bj][1][0] * v[bj][1][0] + v[bj][1][1] * v[bj][1][1]) + (v[bj][1][2] * v[bj][1][2] + v[bj][1][3] * v[bj][1][3]); }
;                     ss += __shfl_xor(ss, 16); ss += __shfl_xor(ss, 32);
;                     const float rh = ttype < 2 ? rsqrtf(ss * (1.f / 64.f) + 1e-6f) : 1.f;
; #pragma unroll
;                     for (int bj = 0; bj < 2; ++bj) {
;                         u32x4 w; w.x = cvt_pk_bf16(v[bj][0][0] * rh * gv[bj][0], v[bj][0][1] * rh * gv[bj][1]); w.y = cvt_pk_bf16(v[bj][0][2] * rh * gv[bj][2], v[bj][0][3] * rh * gv[bj][3]);
;                         w.z = cvt_pk_bf16(v[bj][1][0] * rh * gv[bj][4], v[bj][1][1] * rh * gv[bj][5]); w.w = cvt_pk_bf16(v[bj][1][2] * rh * gv[bj][6], v[bj][1][3] * rh * gv[bj][7]);
;                         *(u32x4*)(O + (size_t)row * ldc + colo + 32 * bj) = w;
.LBB0_991:
	v_mul_f32_e32 v28, v28, v34
	v_mul_f32_e32 v29, v29, v34
	v_mul_f32_e32 v28, v152, v28
	v_mul_f32_e32 v29, v153, v29
	v_cvt_pk_bf16_f32 v28, v28, v29
	v_mul_f32_e32 v29, v30, v34
	v_mul_f32_e32 v30, v31, v34
	v_mul_f32_e32 v24, v24, v34
	v_mul_f32_e32 v25, v25, v34
	v_mul_f32_e32 v29, v154, v29
	v_mul_f32_e32 v30, v155, v30
	v_mul_f32_e32 v24, v156, v24
	v_mul_f32_e32 v25, v157, v25
	v_cvt_pk_bf16_f32 v29, v29, v30
	v_cvt_pk_bf16_f32 v30, v24, v25
	v_mul_f32_e32 v24, v26, v34
	v_mul_f32_e32 v25, v27, v34
	v_mul_f32_e32 v24, v158, v24
	v_mul_f32_e32 v25, v159, v25
	v_cvt_pk_bf16_f32 v31, v24, v25
	v_mul_lo_u32 v26, s77, v32
	v_mul_lo_u32 v27, s76, v33
	v_mad_u64_u32 v[24:25], s[0:1], s76, v32, 0
	v_add3_u32 v25, v25, v27, v26
	v_lshl_add_u64 v[24:25], v[24:25], 1, s[80:81]
	v_mul_f32_e32 v20, v20, v34
	v_mul_f32_e32 v21, v21, v34
	v_lshl_add_u64 v[24:25], v[112:113], 1, v[24:25]
	v_mul_f32_e32 v20, v160, v20
	v_mul_f32_e32 v21, v161, v21
	global_store_dwordx4 v[24:25], v[28:31], off
	v_cvt_pk_bf16_f32 v20, v20, v21
	v_mul_f32_e32 v21, v22, v34
	v_mul_f32_e32 v22, v23, v34
	v_mul_f32_e32 v16, v16, v34
	v_mul_f32_e32 v21, v162, v21
	v_mul_f32_e32 v22, v163, v22
	v_mul_f32_e32 v16, v164, v16
	v_mul_f32_e32 v17, v17, v34
	v_cvt_pk_bf16_f32 v21, v21, v22
	v_mul_f32_e32 v17, v165, v17
	v_cvt_pk_bf16_f32 v22, v16, v17
	v_mul_f32_e32 v16, v18, v34
	v_mul_f32_e32 v16, v166, v16
	v_mul_f32_e32 v17, v19, v34
	v_mul_f32_e32 v17, v167, v17
	v_cvt_pk_bf16_f32 v23, v16, v17
	v_add_u32_e32 v16, 0xb0, v148
	v_mov_b32_e32 v18, 0
	v_ashrrev_i32_e32 v17, 31, v16
	global_store_dwordx4 v[24:25], v[20:23], off offset:64
	s_and_saveexec_b64 s[0:1], s[40:41]
	s_cbranch_execz .LBB0_993
	v_lshlrev_b64 v[18:19], 6, v[16:17]
	v_lshl_add_u64 v[18:19], v[138:139], 0, v[18:19]
	v_mov_b32_e32 v18, v234
	v_mov_b32_e32 v19, v235
	v_mov_b32_e32 v20, v236
	v_mov_b32_e32 v21, v237
	v_mov_b32_e32 v22, v19
	v_mov_b32_e32 v23, v20
	v_mov_b32_e32 v19, v21
	v_pk_add_f32 v[18:19], v[22:23], v[18:19]
	s_nop 0
	v_add_f32_e32 v18, v18, v19
